# more of the weight conversion moved out of phase 0: SSD / attention / FFN weights of later layers converted in the FFN-up tails of layers 0-2
# speedup vs baseline: 1.0057x; 1.0019x over previous
.LBB0_59:
	s_or_b64 exec, exec, s[0:1]
	s_mov_b32 s3, s24
	s_load_dwordx2 s[38:39], s[60:61], 0x8
	s_load_dwordx2 s[40:41], s[60:61], 0x10
	s_load_dwordx2 s[42:43], s[60:61], 0x30
	s_load_dwordx2 s[44:45], s[60:61], 0x38
	s_load_dwordx2 s[48:49], s[60:61], 0x40
	s_load_dwordx2 s[50:51], s[60:61], 0x78
	s_load_dwordx2 s[52:53], s[60:61], 0x80
	s_load_dwordx2 s[54:55], s[60:61], 0x88
	s_load_dwordx2 s[56:57], s[60:61], 0xa0
	v_lshrrev_b32_e32 v8, 6, v175
	v_and_b32_e32 v9, 63, v175
	v_lshrrev_b32_e32 v1, 3, v9
	v_and_b32_e32 v2, 7, v9
	v_readfirstlane_b32 s20, v8
	v_lshlrev_b32_e32 v5, 5, v1
	v_lshlrev_b32_e32 v10, 14, v8
	v_mul_u32_u24_e32 v11, 33, v1
	v_lshl_add_u32 v11, v2, 2, v11
	v_lshl_add_u32 v3, v11, 2, v10
	v_mul_u32_u24_e32 v11, 264, v1
	v_add_u32_e32 v11, v11, v2
	v_lshl_add_u32 v4, v11, 2, v10
	v_mov_b32_e32 v16, 0
	v_mov_b32_e32 v17, 0
	v_mov_b32_e32 v18, 0
	v_mov_b32_e32 v19, 0
	v_lshl_add_u32 v12, s3, 9, v175
	v_lshlrev_b32_e32 v13, 4, v12
	s_movk_i32 s21, 0x6000
	v_cmp_gt_u32_e32 vcc, s21, v12
	s_and_saveexec_b64 s[22:23], vcc
	s_add_u32 s0, s36, 0x1820000
	s_addc_u32 s1, s37, 0
	global_store_dwordx4 v13, v[16:19], s[0:1]
	s_add_u32 s0, s0, 0x1080000
	s_addc_u32 s1, s1, 0
	global_store_dwordx4 v13, v[16:19], s[0:1]
	s_mov_b64 exec, s[22:23]
	s_lshl_b32 s2, s3, 3
	s_add_u32 s2, s2, s20
	s_waitcnt lgkmcnt(0)
	s_cmp_lt_u32 s2, 5504
	s_cselect_b32 s10, 1, 0
	s_cselect_b32 s20, s2, 0
	s_cmp_lt_u32 s20, 1280
	s_cselect_b32 s21, 0, 9536
	s_add_u32 s20, s20, s21
	s_cmp_lt_u32 s20, 10816
	s_cbranch_scc0 .Lp0_ffn_1
	s_cmp_lt_u32 s20, 5408
	s_cselect_b32 s21, 0, 1
	s_cselect_b32 s22, 0, 5408
	s_sub_u32 s20, s20, s22
	s_cmp_lt_u32 s20, 768
	s_cbranch_scc1 .Lp0_k0_3
	s_sub_u32 s20, s20, 768
	s_cmp_lt_u32 s20, 512
	s_cbranch_scc1 .Lp0_k1_4
	s_sub_u32 s20, s20, 512
	s_cmp_lt_u32 s20, 3104
	s_cbranch_scc1 .Lp0_k2_5
	s_sub_u32 s20, s20, 3104
	s_branch .Lp0_k3_6

.Lp0_go_9:
	v_lshlrev_b32_e32 v6, 4, v2
	v_mad_u32_u24 v6, v1, s29, v6
	s_lshl_b32 s29, s29, 3
	global_load_dwordx4 v[56:59], v6, s[26:27] nt
	s_add_u32 s26, s26, s29
	s_addc_u32 s27, s27, 0
	global_load_dwordx4 v[60:63], v6, s[26:27] nt
	s_add_u32 s26, s26, s29
	s_addc_u32 s27, s27, 0
	global_load_dwordx4 v[64:67], v6, s[26:27] nt
	s_add_u32 s26, s26, s29
	s_addc_u32 s27, s27, 0
	global_load_dwordx4 v[68:71], v6, s[26:27] nt
	s_add_u32 s26, s26, s29
	s_addc_u32 s27, s27, 0
	global_load_dwordx4 v[72:75], v6, s[26:27] nt
	s_add_u32 s26, s26, s29
	s_addc_u32 s27, s27, 0
	global_load_dwordx4 v[76:79], v6, s[26:27] nt
	s_add_u32 s26, s26, s29
	s_addc_u32 s27, s27, 0
	global_load_dwordx4 v[80:83], v6, s[26:27] nt
	s_add_u32 s26, s26, s29
	s_addc_u32 s27, s27, 0
	global_load_dwordx4 v[84:87], v6, s[26:27] nt
	global_load_dwordx4 v[88:91], v5, s[8:9]
	global_load_dwordx4 v[92:95], v5, s[8:9] offset:16
	s_add_u32 s2, s2, s28
	s_cmp_lt_u32 s2, 5504
	s_cselect_b32 s18, 1, 0
	s_cselect_b32 s20, s2, 0
	s_cmp_lt_u32 s20, 1280
	s_cselect_b32 s21, 0, 9536
	s_add_u32 s20, s20, s21
	s_cmp_lt_u32 s20, 10816
	s_cbranch_scc0 .Lp0_ffn_10
	s_cmp_lt_u32 s20, 5408
	s_cselect_b32 s21, 0, 1
	s_cselect_b32 s22, 0, 5408
	s_sub_u32 s20, s20, s22
	s_cmp_lt_u32 s20, 768
	s_cbranch_scc1 .Lp0_k0_12
	s_sub_u32 s20, s20, 768
	s_cmp_lt_u32 s20, 512
	s_cbranch_scc1 .Lp0_k1_13
	s_sub_u32 s20, s20, 512
	s_cmp_lt_u32 s20, 3104
	s_cbranch_scc1 .Lp0_k2_14
	s_sub_u32 s20, s20, 3104
	s_branch .Lp0_k3_15

.Lp0_loop:
	s_add_u32 s2, s2, s28
	s_cmp_lt_u32 s2, 5504
	s_cselect_b32 s10, 1, 0
	s_cselect_b32 s20, s2, 0
	s_cmp_lt_u32 s20, 1280
	s_cselect_b32 s21, 0, 9536
	s_add_u32 s20, s20, s21
	s_cmp_lt_u32 s20, 10816
	s_cbranch_scc0 .Lp0_ffn_20
	s_cmp_lt_u32 s20, 5408
	s_cselect_b32 s21, 0, 1
	s_cselect_b32 s22, 0, 5408
	s_sub_u32 s20, s20, s22
	s_cmp_lt_u32 s20, 768
	s_cbranch_scc1 .Lp0_k0_22
	s_sub_u32 s20, s20, 768
	s_cmp_lt_u32 s20, 512
	s_cbranch_scc1 .Lp0_k1_23
	s_sub_u32 s20, s20, 512
	s_cmp_lt_u32 s20, 3104
	s_cbranch_scc1 .Lp0_k2_24
	s_sub_u32 s20, s20, 3104
	s_branch .Lp0_k3_25

.Lp0_nog_29:
	v_cvt_pk_bf16_f32 v136, v16, v17
	v_cvt_pk_bf16_f32 v137, v18, v19
	v_cvt_pk_bf16_f32 v138, v20, v21
	v_cvt_pk_bf16_f32 v139, v22, v23
	v_cvt_pk_bf16_f32 v140, v24, v25
	v_cvt_pk_bf16_f32 v141, v26, v27
	v_cvt_pk_bf16_f32 v142, v28, v29
	v_cvt_pk_bf16_f32 v143, v30, v31
	v_cvt_pk_bf16_f32 v144, v32, v33
	v_cvt_pk_bf16_f32 v145, v34, v35
	v_cvt_pk_bf16_f32 v146, v36, v37
	v_cvt_pk_bf16_f32 v147, v38, v39
	v_cvt_pk_bf16_f32 v148, v40, v41
	v_cvt_pk_bf16_f32 v149, v42, v43
	v_cvt_pk_bf16_f32 v150, v44, v45
	v_cvt_pk_bf16_f32 v151, v46, v47
	global_store_dwordx4 v7, v[136:139], s[12:13]
	s_add_u32 s12, s12, s20
	s_addc_u32 s13, s13, 0
	global_store_dwordx4 v7, v[140:143], s[12:13]
	s_add_u32 s12, s12, s20
	s_addc_u32 s13, s13, 0
	global_store_dwordx4 v7, v[144:147], s[12:13]
	s_add_u32 s12, s12, s20
	s_addc_u32 s13, s13, 0
	global_store_dwordx4 v7, v[148:151], s[12:13]
	s_add_u32 s2, s2, s28
	s_cmp_lt_u32 s2, 5504
	s_cselect_b32 s18, 1, 0
	s_cselect_b32 s20, s2, 0
	s_cmp_lt_u32 s20, 1280
	s_cselect_b32 s21, 0, 9536
	s_add_u32 s20, s20, s21
	s_cmp_lt_u32 s20, 10816
	s_cbranch_scc0 .Lp0_ffn_30
	s_cmp_lt_u32 s20, 5408
	s_cselect_b32 s21, 0, 1
	s_cselect_b32 s22, 0, 5408
	s_sub_u32 s20, s20, s22
	s_cmp_lt_u32 s20, 768
	s_cbranch_scc1 .Lp0_k0_32
	s_sub_u32 s20, s20, 768
	s_cmp_lt_u32 s20, 512
	s_cbranch_scc1 .Lp0_k1_33
	s_sub_u32 s20, s20, 512
	s_cmp_lt_u32 s20, 3104
	s_cbranch_scc1 .Lp0_k2_34
	s_sub_u32 s20, s20, 3104
	s_branch .Lp0_k3_35

.Ldf_mod_1:
	s_cmp_ge_u32 s7, s6
	s_cselect_b32 s4, s6, 0
	s_sub_u32 s7, s7, s4
	s_cmp_ge_u32 s7, s6
	s_cbranch_scc1 .Ldf_mod_1
	s_cmp_eq_u32 s7, 0
	s_cbranch_scc1 .Ldf_done
	s_cmp_ge_u32 s31, s7
	s_cbranch_scc0 .Ldf_done
	s_waitcnt vmcnt(0) lgkmcnt(0)
	s_barrier
	v_writelane_b32 v255, s96, 7
	v_writelane_b32 v255, s97, 8
	v_writelane_b32 v255, s98, 9
	v_writelane_b32 v255, s99, 10
	v_writelane_b32 v255, s86, 0
	v_writelane_b32 v255, s87, 1
	v_writelane_b32 v255, s42, 11
	v_writelane_b32 v255, s43, 12
	s_mov_b32 s72, s7
	s_cmp_eq_u32 s9, 0
	s_cbranch_scc1 .Ldf_t0_2
	s_cmp_eq_u32 s9, 1
	s_cbranch_scc1 .Ldf_t1_3
.Ldf_t2_4:
	s_movk_i32 s68, 0x1a20
	s_movk_i32 s69, 0x1020
	s_movk_i32 s70, 0x5bc0
	s_movk_i32 s71, 0x20a0
	s_branch .Ldf_tj_5
.Ldf_t1_3:
	s_movk_i32 s68, 0x1520
	s_movk_i32 s69, 0x500
	s_movk_i32 s70, 0x4b40
	s_movk_i32 s71, 0x1580
	s_branch .Ldf_tj_5
.Ldf_t0_2:
	s_movk_i32 s68, 0x500
	s_movk_i32 s69, 0x1020
	s_movk_i32 s70, 0x3ac0
	s_movk_i32 s71, 0x20a0
.Ldf_tj_5:
	s_load_dwordx2 s[42:43], s[60:61], 0x8
	s_load_dwordx2 s[44:45], s[60:61], 0x10
	s_load_dwordx2 s[46:47], s[60:61], 0x30
	s_load_dwordx2 s[48:49], s[60:61], 0x38
	s_load_dwordx2 s[50:51], s[60:61], 0x40
	s_load_dwordx2 s[52:53], s[60:61], 0x78
	s_load_dwordx2 s[54:55], s[60:61], 0x80
	s_load_dwordx2 s[56:57], s[60:61], 0x88
	s_load_dwordx2 s[64:65], s[60:61], 0xa0
	v_lshrrev_b32_e32 v8, 6, v175
	v_and_b32_e32 v9, 63, v175
	v_lshrrev_b32_e32 v1, 3, v9
	v_and_b32_e32 v2, 7, v9
	v_readfirstlane_b32 s21, v8
	v_lshlrev_b32_e32 v5, 5, v1
	v_lshlrev_b32_e32 v10, 14, v8
	v_mul_u32_u24_e32 v11, 33, v1
	v_lshl_add_u32 v11, v2, 2, v11
	v_lshl_add_u32 v3, v11, 2, v10
	v_mul_u32_u24_e32 v11, 264, v1
	v_add_u32_e32 v11, v11, v2
	v_lshl_add_u32 v4, v11, 2, v10
	s_sub_u32 s3, s31, s72
	s_lshl_b32 s3, s3, 3
	s_add_u32 s3, s3, s21
	s_sub_u32 s41, s6, s72
	s_lshl_b32 s41, s41, 3
	s_waitcnt lgkmcnt(0)
	s_cmp_lt_u32 s3, s71
	s_cselect_b32 s10, 1, 0
	s_cselect_b32 s21, s3, 0
	s_cmp_lt_u32 s21, s69
	s_cselect_b32 s22, s68, s70
	s_cselect_b32 s23, 0, s69
	s_sub_u32 s21, s21, s23
	s_add_u32 s21, s21, s22
	s_cmp_lt_u32 s21, 10816
	s_cbranch_scc0 .Ldf_ffn_6
	s_cmp_lt_u32 s21, 5408
	s_cselect_b32 s22, 0, 1
	s_cselect_b32 s23, 0, 5408
	s_sub_u32 s21, s21, s23
	s_cmp_lt_u32 s21, 768
	s_cbranch_scc1 .Ldf_k0_7
	s_sub_u32 s21, s21, 768
	s_cmp_lt_u32 s21, 512
	s_cbranch_scc1 .Ldf_k1_8
	s_sub_u32 s21, s21, 512
	s_cmp_lt_u32 s21, 3104
	s_cbranch_scc1 .Ldf_k2_9
	s_sub_u32 s21, s21, 3104
	s_branch .Ldf_k3_10
.Ldf_ffn_6:
	s_sub_u32 s21, s21, 10816
	s_mov_b32 s22, 0
	s_cmp_lt_u32 s21, 4224
	s_cselect_b32 s23, 0, 4224
	s_cselect_b32 s24, 0, 1
	s_sub_u32 s21, s21, s23
	s_add_u32 s22, s22, s24
	s_cmp_lt_u32 s21, 4224
	s_cselect_b32 s23, 0, 4224
	s_cselect_b32 s24, 0, 1
	s_sub_u32 s21, s21, s23
	s_add_u32 s22, s22, s24
	s_cmp_lt_u32 s21, 4224
	s_cselect_b32 s23, 0, 4224
	s_cselect_b32 s24, 0, 1
	s_sub_u32 s21, s21, s23
	s_add_u32 s22, s22, s24
	s_cmp_lt_u32 s21, 2816
	s_cbranch_scc1 .Ldf_k4_11
	s_sub_u32 s21, s21, 2816
	s_branch .Ldf_k5_12
.Ldf_k0_7:
	s_mul_hi_u32 s23, s21, 0x5555556
	s_mul_i32 s24, s23, 48
	s_sub_u32 s24, s21, s24
	s_lshl_b32 s23, s23, 6
	s_lshl_b32 s24, s24, 5
	s_mul_i32 s25, s22, 0x600000
	s_mul_i32 s26, s23, 6144
	s_add_u32 s25, s25, s26
	s_lshl_b32 s26, s24, 2
	s_add_u32 s25, s25, s26
	s_add_u32 s38, s44, s25
	s_addc_u32 s39, s45, 0
	s_mov_b32 s27, 0x1800
	s_lshl_b32 s25, s22, 12
	s_lshl_b32 s26, s23, 2
	s_add_u32 s25, s25, s26
	s_add_u32 s8, s42, s25
	s_addc_u32 s9, s43, 0
	s_mov_b32 s7, 1
	s_mov_b32 s40, s24
	s_mul_i32 s40, s40, 2048
	s_mul_i32 s25, s22, 0x500000
	s_add_u32 s40, s40, s25
	s_lshl_b32 s25, s23, 1
	s_add_u32 s40, s40, s25
	s_add_u32 s40, s40, 0x200000
	s_add_u32 s4, s36, s40
	s_addc_u32 s5, s37, 0
	s_mov_b32 s6, 0x800
	s_branch .Ldf_go_13
.Ldf_k1_8:
	s_lshr_b32 s23, s21, 5
	s_and_b32 s24, s21, 31
	s_lshl_b32 s23, s23, 6
	s_lshl_b32 s24, s24, 5
	s_mul_i32 s25, s22, 0x400000
	s_mul_i32 s26, s23, 4096
	s_add_u32 s25, s25, s26
	s_lshl_b32 s26, s24, 2
	s_add_u32 s25, s25, s26
	s_add_u32 s38, s46, s25
	s_addc_u32 s39, s47, 0
	s_mov_b32 s27, 0x1000
	s_mov_b32 s8, s38
	s_mov_b32 s9, s39
	s_mov_b32 s7, 0
	s_mov_b32 s40, s24
	s_mul_i32 s40, s40, 2048
	s_mul_i32 s25, s22, 0x500000
	s_add_u32 s40, s40, s25
	s_lshl_b32 s25, s23, 1
	s_add_u32 s40, s40, s25
	s_add_u32 s40, s40, 0x500000
	s_add_u32 s4, s36, s40
	s_addc_u32 s5, s37, 0
	s_mov_b32 s6, 0x800
	s_branch .Ldf_go_13
.Ldf_k2_9:
	s_mul_hi_u32 s23, s21, 0x151d07f
	s_mul_i32 s24, s23, 194
	s_sub_u32 s24, s21, s24
	s_lshl_b32 s23, s23, 6
	s_lshl_b32 s24, s24, 5
	s_mul_i32 s25, s22, 0x1840000
	s_mul_i32 s26, s23, 24832
	s_add_u32 s25, s25, s26
	s_lshl_b32 s26, s24, 2
	s_add_u32 s25, s25, s26
	s_add_u32 s38, s50, s25
	s_addc_u32 s39, s51, 0
	s_mov_b32 s27, 0x6100
	s_lshl_b32 s25, s22, 12
	s_lshl_b32 s26, s23, 2
	s_add_u32 s25, s25, s26
	s_add_u32 s8, s48, s25
	s_addc_u32 s9, s49, 0
	s_mov_b32 s7, 1
	s_mov_b32 s40, s24
	s_mul_i32 s40, s40, 2048
	s_mul_i32 s25, s22, 0x1080000
	s_add_u32 s40, s40, s25
	s_lshl_b32 s25, s23, 1
	s_add_u32 s40, s40, s25
	s_add_u32 s40, s40, 0xc00000
	s_add_u32 s4, s36, s40
	s_addc_u32 s5, s37, 0
	s_mov_b32 s6, 0x800
	s_branch .Ldf_go_13
.Ldf_k3_10:
	s_lshr_b32 s23, s21, 5
	s_and_b32 s24, s21, 31
	s_lshl_b32 s23, s23, 6
	s_lshl_b32 s24, s24, 5
	s_mul_i32 s25, s22, 0x800000
	s_mul_i32 s26, s23, 4096
	s_add_u32 s25, s25, s26
	s_lshl_b32 s26, s24, 2
	s_add_u32 s25, s25, s26
	s_add_u32 s38, s52, s25
	s_addc_u32 s39, s53, 0
	s_mov_b32 s27, 0x1000
	s_mov_b32 s8, s38
	s_mov_b32 s9, s39
	s_mov_b32 s7, 0
	s_mov_b32 s40, s24
	s_mul_i32 s40, s40, 4096
	s_mul_i32 s25, s22, 0x1080000
	s_add_u32 s40, s40, s25
	s_lshl_b32 s25, s23, 1
	s_add_u32 s40, s40, s25
	s_add_u32 s40, s40, 0x1880000
	s_add_u32 s4, s36, s40
	s_addc_u32 s5, s37, 0
	s_mov_b32 s6, 0x1000
	s_branch .Ldf_go_13
.Ldf_k4_11:
	s_mul_hi_u32 s23, s21, 0x1745d18
	s_mul_i32 s24, s23, 176
	s_sub_u32 s24, s21, s24
	s_lshl_b32 s23, s23, 6
	s_lshl_b32 s24, s24, 5
	s_mul_i32 s25, s22, 0x1600000
	s_mul_i32 s26, s23, 22528
	s_add_u32 s25, s25, s26
	s_lshl_b32 s26, s24, 2
	s_add_u32 s25, s25, s26
	s_add_u32 s38, s56, s25
	s_addc_u32 s39, s57, 0
	s_mov_b32 s27, 0x5800
	s_lshl_b32 s25, s22, 12
	s_lshl_b32 s26, s23, 2
	s_add_u32 s25, s25, s26
	s_add_u32 s8, s54, s25
	s_addc_u32 s9, s55, 0
	s_mov_b32 s7, 1
	s_cmp_lt_u32 s24, 2816
	s_cselect_b32 s25, 0, 2816
	s_cselect_b32 s26, 0, 128
	s_sub_u32 s25, s24, s25
	s_lshr_b32 s40, s25, 7
	s_lshl_b32 s40, s40, 8
	s_and_b32 s25, s25, 127
	s_add_u32 s40, s40, s25
	s_add_u32 s40, s40, s26
	s_mul_i32 s40, s40, 2048
	s_mul_i32 s25, s22, 0x1080000
	s_add_u32 s40, s40, s25
	s_lshl_b32 s25, s23, 1
	s_add_u32 s40, s40, s25
	s_add_u32 s40, s40, 0x2d00000
	s_add_u32 s4, s36, s40
	s_addc_u32 s5, s37, 0
	s_mov_b32 s6, 0x800
	s_branch .Ldf_go_13
.Ldf_k5_12:
	s_lshr_b32 s23, s21, 5
	s_and_b32 s24, s21, 31
	s_lshl_b32 s23, s23, 6
	s_lshl_b32 s24, s24, 5
	s_mul_i32 s25, s22, 0xb00000
	s_mul_i32 s26, s23, 4096
	s_add_u32 s25, s25, s26
	s_lshl_b32 s26, s24, 2
	s_add_u32 s25, s25, s26
	s_add_u32 s38, s64, s25
	s_addc_u32 s39, s65, 0
	s_mov_b32 s27, 0x1000
	s_mov_b32 s8, s38
	s_mov_b32 s9, s39
	s_mov_b32 s7, 0
	s_mov_b32 s40, s24
	s_mul_i32 s40, s40, 5632
	s_mul_i32 s25, s22, 0x1080000
	s_add_u32 s40, s40, s25
	s_lshl_b32 s25, s23, 1
	s_add_u32 s40, s40, s25
	s_add_u32 s40, s40, 0x3800000
	s_add_u32 s4, s36, s40
	s_addc_u32 s5, s37, 0
	s_mov_b32 s6, 0x1600
.Ldf_go_13:
	v_lshlrev_b32_e32 v6, 4, v2
	v_mad_u32_u24 v6, v1, s27, v6
	s_lshl_b32 s27, s27, 3
	global_load_dwordx4 v[56:59], v6, s[38:39] nt
	s_add_u32 s38, s38, s27
	s_addc_u32 s39, s39, 0
	global_load_dwordx4 v[60:63], v6, s[38:39] nt
	s_add_u32 s38, s38, s27
	s_addc_u32 s39, s39, 0
	global_load_dwordx4 v[64:67], v6, s[38:39] nt
	s_add_u32 s38, s38, s27
	s_addc_u32 s39, s39, 0
	global_load_dwordx4 v[68:71], v6, s[38:39] nt
	s_add_u32 s38, s38, s27
	s_addc_u32 s39, s39, 0
	global_load_dwordx4 v[72:75], v6, s[38:39] nt
	s_add_u32 s38, s38, s27
	s_addc_u32 s39, s39, 0
	global_load_dwordx4 v[76:79], v6, s[38:39] nt
	s_add_u32 s38, s38, s27
	s_addc_u32 s39, s39, 0
	global_load_dwordx4 v[80:83], v6, s[38:39] nt
	s_add_u32 s38, s38, s27
	s_addc_u32 s39, s39, 0
	global_load_dwordx4 v[84:87], v6, s[38:39] nt
	global_load_dwordx4 v[88:91], v5, s[8:9]
	global_load_dwordx4 v[92:95], v5, s[8:9] offset:16
	s_add_u32 s3, s3, s41
	s_cmp_lt_u32 s3, s71
	s_cselect_b32 s20, 1, 0
	s_cselect_b32 s21, s3, 0
	s_cmp_lt_u32 s21, s69
	s_cselect_b32 s22, s68, s70
	s_cselect_b32 s23, 0, s69
	s_sub_u32 s21, s21, s23
	s_add_u32 s21, s21, s22
	s_cmp_lt_u32 s21, 10816
	s_cbranch_scc0 .Ldf_ffn_14
	s_cmp_lt_u32 s21, 5408
	s_cselect_b32 s22, 0, 1
	s_cselect_b32 s23, 0, 5408
	s_sub_u32 s21, s21, s23
	s_cmp_lt_u32 s21, 768
	s_cbranch_scc1 .Ldf_k0_15
	s_sub_u32 s21, s21, 768
	s_cmp_lt_u32 s21, 512
	s_cbranch_scc1 .Ldf_k1_16
	s_sub_u32 s21, s21, 512
	s_cmp_lt_u32 s21, 3104
	s_cbranch_scc1 .Ldf_k2_17
	s_sub_u32 s21, s21, 3104
	s_branch .Ldf_k3_18

.Ldf_k0_15:
	s_mul_hi_u32 s23, s21, 0x5555556
	s_mul_i32 s24, s23, 48
	s_sub_u32 s24, s21, s24
	s_lshl_b32 s23, s23, 6
	s_lshl_b32 s24, s24, 5
	s_mul_i32 s25, s22, 0x600000
	s_mul_i32 s26, s23, 6144
	s_add_u32 s25, s25, s26
	s_lshl_b32 s26, s24, 2
	s_add_u32 s25, s25, s26
	s_add_u32 s38, s44, s25
	s_addc_u32 s39, s45, 0
	s_mov_b32 s27, 0x1800
	s_lshl_b32 s25, s22, 12
	s_lshl_b32 s26, s23, 2
	s_add_u32 s25, s25, s26
	s_add_u32 s18, s42, s25
	s_addc_u32 s19, s43, 0
	s_mov_b32 s17, 1
	s_mov_b32 s40, s24
	s_mul_i32 s40, s40, 2048
	s_mul_i32 s25, s22, 0x500000
	s_add_u32 s40, s40, s25
	s_lshl_b32 s25, s23, 1
	s_add_u32 s40, s40, s25
	s_add_u32 s40, s40, 0x200000
	s_add_u32 s14, s36, s40
	s_addc_u32 s15, s37, 0
	s_mov_b32 s16, 0x800
	s_branch .Ldf_go_21
.Ldf_k1_16:
	s_lshr_b32 s23, s21, 5
	s_and_b32 s24, s21, 31
	s_lshl_b32 s23, s23, 6
	s_lshl_b32 s24, s24, 5
	s_mul_i32 s25, s22, 0x400000
	s_mul_i32 s26, s23, 4096
	s_add_u32 s25, s25, s26
	s_lshl_b32 s26, s24, 2
	s_add_u32 s25, s25, s26
	s_add_u32 s38, s46, s25
	s_addc_u32 s39, s47, 0
	s_mov_b32 s27, 0x1000
	s_mov_b32 s18, s38
	s_mov_b32 s19, s39
	s_mov_b32 s17, 0
	s_mov_b32 s40, s24
	s_mul_i32 s40, s40, 2048
	s_mul_i32 s25, s22, 0x500000
	s_add_u32 s40, s40, s25
	s_lshl_b32 s25, s23, 1
	s_add_u32 s40, s40, s25
	s_add_u32 s40, s40, 0x500000
	s_add_u32 s14, s36, s40
	s_addc_u32 s15, s37, 0
	s_mov_b32 s16, 0x800
	s_branch .Ldf_go_21
.Ldf_k2_17:
	s_mul_hi_u32 s23, s21, 0x151d07f
	s_mul_i32 s24, s23, 194
	s_sub_u32 s24, s21, s24
	s_lshl_b32 s23, s23, 6
	s_lshl_b32 s24, s24, 5
	s_mul_i32 s25, s22, 0x1840000
	s_mul_i32 s26, s23, 24832
	s_add_u32 s25, s25, s26
	s_lshl_b32 s26, s24, 2
	s_add_u32 s25, s25, s26
	s_add_u32 s38, s50, s25
	s_addc_u32 s39, s51, 0
	s_mov_b32 s27, 0x6100
	s_lshl_b32 s25, s22, 12
	s_lshl_b32 s26, s23, 2
	s_add_u32 s25, s25, s26
	s_add_u32 s18, s48, s25
	s_addc_u32 s19, s49, 0
	s_mov_b32 s17, 1
	s_mov_b32 s40, s24
	s_mul_i32 s40, s40, 2048
	s_mul_i32 s25, s22, 0x1080000
	s_add_u32 s40, s40, s25
	s_lshl_b32 s25, s23, 1
	s_add_u32 s40, s40, s25
	s_add_u32 s40, s40, 0xc00000
	s_add_u32 s14, s36, s40
	s_addc_u32 s15, s37, 0
	s_mov_b32 s16, 0x800
	s_branch .Ldf_go_21
.Ldf_k3_18:
	s_lshr_b32 s23, s21, 5
	s_and_b32 s24, s21, 31
	s_lshl_b32 s23, s23, 6
	s_lshl_b32 s24, s24, 5
	s_mul_i32 s25, s22, 0x800000
	s_mul_i32 s26, s23, 4096
	s_add_u32 s25, s25, s26
	s_lshl_b32 s26, s24, 2
	s_add_u32 s25, s25, s26
	s_add_u32 s38, s52, s25
	s_addc_u32 s39, s53, 0
	s_mov_b32 s27, 0x1000
	s_mov_b32 s18, s38
	s_mov_b32 s19, s39
	s_mov_b32 s17, 0
	s_mov_b32 s40, s24
	s_mul_i32 s40, s40, 4096
	s_mul_i32 s25, s22, 0x1080000
	s_add_u32 s40, s40, s25
	s_lshl_b32 s25, s23, 1
	s_add_u32 s40, s40, s25
	s_add_u32 s40, s40, 0x1880000
	s_add_u32 s14, s36, s40
	s_addc_u32 s15, s37, 0
	s_mov_b32 s16, 0x1000
	s_branch .Ldf_go_21
.Ldf_k4_19:
	s_mul_hi_u32 s23, s21, 0x1745d18
	s_mul_i32 s24, s23, 176
	s_sub_u32 s24, s21, s24
	s_lshl_b32 s23, s23, 6
	s_lshl_b32 s24, s24, 5
	s_mul_i32 s25, s22, 0x1600000
	s_mul_i32 s26, s23, 22528
	s_add_u32 s25, s25, s26
	s_lshl_b32 s26, s24, 2
	s_add_u32 s25, s25, s26
	s_add_u32 s38, s56, s25
	s_addc_u32 s39, s57, 0
	s_mov_b32 s27, 0x5800
	s_lshl_b32 s25, s22, 12
	s_lshl_b32 s26, s23, 2
	s_add_u32 s25, s25, s26
	s_add_u32 s18, s54, s25
	s_addc_u32 s19, s55, 0
	s_mov_b32 s17, 1
	s_cmp_lt_u32 s24, 2816
	s_cselect_b32 s25, 0, 2816
	s_cselect_b32 s26, 0, 128
	s_sub_u32 s25, s24, s25
	s_lshr_b32 s40, s25, 7
	s_lshl_b32 s40, s40, 8
	s_and_b32 s25, s25, 127
	s_add_u32 s40, s40, s25
	s_add_u32 s40, s40, s26
	s_mul_i32 s40, s40, 2048
	s_mul_i32 s25, s22, 0x1080000
	s_add_u32 s40, s40, s25
	s_lshl_b32 s25, s23, 1
	s_add_u32 s40, s40, s25
	s_add_u32 s40, s40, 0x2d00000
	s_add_u32 s14, s36, s40
	s_addc_u32 s15, s37, 0
	s_mov_b32 s16, 0x800
	s_branch .Ldf_go_21
.Ldf_k5_20:
	s_lshr_b32 s23, s21, 5
	s_and_b32 s24, s21, 31
	s_lshl_b32 s23, s23, 6
	s_lshl_b32 s24, s24, 5
	s_mul_i32 s25, s22, 0xb00000
	s_mul_i32 s26, s23, 4096
	s_add_u32 s25, s25, s26
	s_lshl_b32 s26, s24, 2
	s_add_u32 s25, s25, s26
	s_add_u32 s38, s64, s25
	s_addc_u32 s39, s65, 0
	s_mov_b32 s27, 0x1000
	s_mov_b32 s18, s38
	s_mov_b32 s19, s39
	s_mov_b32 s17, 0
	s_mov_b32 s40, s24
	s_mul_i32 s40, s40, 5632
	s_mul_i32 s25, s22, 0x1080000
	s_add_u32 s40, s40, s25
	s_lshl_b32 s25, s23, 1
	s_add_u32 s40, s40, s25
	s_add_u32 s40, s40, 0x3800000
	s_add_u32 s14, s36, s40
	s_addc_u32 s15, s37, 0
	s_mov_b32 s16, 0x1600

.Ldf_loop:
	s_add_u32 s3, s3, s41
	s_cmp_lt_u32 s3, s71
	s_cselect_b32 s10, 1, 0
	s_cselect_b32 s21, s3, 0
	s_cmp_lt_u32 s21, s69
	s_cselect_b32 s22, s68, s70
	s_cselect_b32 s23, 0, s69
	s_sub_u32 s21, s21, s23
	s_add_u32 s21, s21, s22
	s_cmp_lt_u32 s21, 10816
	s_cbranch_scc0 .Ldf_ffn_23
	s_cmp_lt_u32 s21, 5408
	s_cselect_b32 s22, 0, 1
	s_cselect_b32 s23, 0, 5408
	s_sub_u32 s21, s21, s23
	s_cmp_lt_u32 s21, 768
	s_cbranch_scc1 .Ldf_k0_24
	s_sub_u32 s21, s21, 768
	s_cmp_lt_u32 s21, 512
	s_cbranch_scc1 .Ldf_k1_25
	s_sub_u32 s21, s21, 512
	s_cmp_lt_u32 s21, 3104
	s_cbranch_scc1 .Ldf_k2_26
	s_sub_u32 s21, s21, 3104
	s_branch .Ldf_k3_27

.Ldf_nog_31:
	v_cvt_pk_bf16_f32 v156, v16, v17
	v_cvt_pk_bf16_f32 v157, v18, v19
	v_cvt_pk_bf16_f32 v158, v20, v21
	v_cvt_pk_bf16_f32 v159, v22, v23
	v_cvt_pk_bf16_f32 v160, v24, v25
	v_cvt_pk_bf16_f32 v161, v26, v27
	v_cvt_pk_bf16_f32 v162, v28, v29
	v_cvt_pk_bf16_f32 v163, v30, v31
	v_cvt_pk_bf16_f32 v164, v32, v33
	v_cvt_pk_bf16_f32 v165, v34, v35
	v_cvt_pk_bf16_f32 v166, v36, v37
	v_cvt_pk_bf16_f32 v167, v38, v39
	v_cvt_pk_bf16_f32 v168, v40, v41
	v_cvt_pk_bf16_f32 v169, v42, v43
	v_cvt_pk_bf16_f32 v170, v44, v45
	v_cvt_pk_bf16_f32 v171, v46, v47
	global_store_dwordx4 v7, v[156:159], s[14:15]
	s_add_u32 s14, s14, s21
	s_addc_u32 s15, s15, 0
	global_store_dwordx4 v7, v[160:163], s[14:15]
	s_add_u32 s14, s14, s21
	s_addc_u32 s15, s15, 0
	global_store_dwordx4 v7, v[164:167], s[14:15]
	s_add_u32 s14, s14, s21
	s_addc_u32 s15, s15, 0
	global_store_dwordx4 v7, v[168:171], s[14:15]
	s_add_u32 s3, s3, s41
	s_cmp_lt_u32 s3, s71
	s_cselect_b32 s20, 1, 0
	s_cselect_b32 s21, s3, 0
	s_cmp_lt_u32 s21, s69
	s_cselect_b32 s22, s68, s70
	s_cselect_b32 s23, 0, s69
	s_sub_u32 s21, s21, s23
	s_add_u32 s21, s21, s22
	s_cmp_lt_u32 s21, 10816
	s_cbranch_scc0 .Ldf_ffn_32
	s_cmp_lt_u32 s21, 5408
	s_cselect_b32 s22, 0, 1
	s_cselect_b32 s23, 0, 5408
	s_sub_u32 s21, s21, s23
	s_cmp_lt_u32 s21, 768
	s_cbranch_scc1 .Ldf_k0_33
	s_sub_u32 s21, s21, 768
	s_cmp_lt_u32 s21, 512
	s_cbranch_scc1 .Ldf_k1_34
	s_sub_u32 s21, s21, 512
	s_cmp_lt_u32 s21, 3104
	s_cbranch_scc1 .Ldf_k2_35
	s_sub_u32 s21, s21, 3104
	s_branch .Ldf_k3_36
